# convert read phase: LDS transposed reads paired into ds_read2_b32 (half the LDS read instructions)
# baseline (speedup 1.0000x reference)
; #define LAS __attribute__((address_space(3)))
; __device__ __forceinline__ unsigned pk2(float lo, float hi) { return pg8::cvt_pk_bf16(lo, hi); }
; #define LDS_WAIT() asm volatile("s_waitcnt lgkmcnt(0)" ::: "memory")
;     ...
;     LDS_WAIT();
;     const int c = lane & 7;
; #pragma unroll
;     for (int j = 0; j < 4; ++j) { const int n = (lane >> 3) + 8 * j; const LAS float* s = scr + (8 * c) * 33 + n;
;         u32x4 o; o.x = pk2(s[0 * 33] * sc, s[1 * 33] * sc); o.y = pk2(s[2 * 33] * sc, s[3 * 33] * sc); o.z = pk2(s[4 * 33] * sc, s[5 * 33] * sc); o.w = pk2(s[6 * 33] * sc, s[7 * 33] * sc);
;         *(u32x4*)(WT + (size_t)(outrow0 + n) * K + k0 + 8 * c) = o; }
;     LDS_WAIT();
.Lcv_nonext:
	v_mad_u32_u24 v6, v1, s53, v2
	s_lshl_b32 s0, s53, 3
	s_waitcnt lgkmcnt(0)
	ds_read2_b32 v[40:41], v4 offset0:0 offset1:33
	ds_read2_b32 v[42:43], v4 offset0:66 offset1:99
	ds_read2_b32 v[44:45], v4 offset0:132 offset1:165
	ds_read2_b32 v[46:47], v4 offset0:198 offset1:231
	s_waitcnt lgkmcnt(0)
	v_mul_f32_e32 v40, s50, v40
	v_mul_f32_e32 v41, s50, v41
	v_mul_f32_e32 v42, s50, v42
	v_mul_f32_e32 v43, s50, v43
	v_mul_f32_e32 v44, s50, v44
	v_mul_f32_e32 v45, s50, v45
	v_mul_f32_e32 v46, s50, v46
	v_mul_f32_e32 v47, s50, v47
	v_cvt_pk_bf16_f32 v48, v40, v41
	v_cvt_pk_bf16_f32 v49, v42, v43
	v_cvt_pk_bf16_f32 v50, v44, v45
	v_cvt_pk_bf16_f32 v51, v46, v47
	global_store_dwordx4 v6, v[48:51], s[56:57]
	v_add_u32_e32 v6, s0, v6
	ds_read2_b32 v[40:41], v4 offset0:8 offset1:41
	ds_read2_b32 v[42:43], v4 offset0:74 offset1:107
	ds_read2_b32 v[44:45], v4 offset0:140 offset1:173
	ds_read2_b32 v[46:47], v4 offset0:206 offset1:239
	s_waitcnt lgkmcnt(0)
	v_mul_f32_e32 v40, s50, v40
	v_mul_f32_e32 v41, s50, v41
	v_mul_f32_e32 v42, s50, v42
	v_mul_f32_e32 v43, s50, v43
	v_mul_f32_e32 v44, s50, v44
	v_mul_f32_e32 v45, s50, v45
	v_mul_f32_e32 v46, s50, v46
	v_mul_f32_e32 v47, s50, v47
	v_cvt_pk_bf16_f32 v48, v40, v41
	v_cvt_pk_bf16_f32 v49, v42, v43
	v_cvt_pk_bf16_f32 v50, v44, v45
	v_cvt_pk_bf16_f32 v51, v46, v47
	global_store_dwordx4 v6, v[48:51], s[56:57]
	v_add_u32_e32 v6, s0, v6
	ds_read2_b32 v[40:41], v4 offset0:16 offset1:49
	ds_read2_b32 v[42:43], v4 offset0:82 offset1:115
	ds_read2_b32 v[44:45], v4 offset0:148 offset1:181
	ds_read2_b32 v[46:47], v4 offset0:214 offset1:247
	s_waitcnt lgkmcnt(0)
	v_mul_f32_e32 v40, s50, v40
	v_mul_f32_e32 v41, s50, v41
	v_mul_f32_e32 v42, s50, v42
	v_mul_f32_e32 v43, s50, v43
	v_mul_f32_e32 v44, s50, v44
	v_mul_f32_e32 v45, s50, v45
	v_mul_f32_e32 v46, s50, v46
	v_mul_f32_e32 v47, s50, v47
	v_cvt_pk_bf16_f32 v48, v40, v41
	v_cvt_pk_bf16_f32 v49, v42, v43
	v_cvt_pk_bf16_f32 v50, v44, v45
	v_cvt_pk_bf16_f32 v51, v46, v47
	global_store_dwordx4 v6, v[48:51], s[56:57]
	v_add_u32_e32 v6, s0, v6
	ds_read2_b32 v[40:41], v4 offset0:24 offset1:57
	ds_read2_b32 v[42:43], v4 offset0:90 offset1:123
	ds_read2_b32 v[44:45], v4 offset0:156 offset1:189
	ds_read2_b32 v[46:47], v4 offset0:222 offset1:255
	s_waitcnt lgkmcnt(0)
	v_mul_f32_e32 v40, s50, v40
	v_mul_f32_e32 v41, s50, v41
	v_mul_f32_e32 v42, s50, v42
	v_mul_f32_e32 v43, s50, v43
	v_mul_f32_e32 v44, s50, v44
	v_mul_f32_e32 v45, s50, v45
	v_mul_f32_e32 v46, s50, v46
	v_mul_f32_e32 v47, s50, v47
	v_cvt_pk_bf16_f32 v48, v40, v41
	v_cvt_pk_bf16_f32 v49, v42, v43
	v_cvt_pk_bf16_f32 v50, v44, v45
	v_cvt_pk_bf16_f32 v51, v46, v47
	global_store_dwordx4 v6, v[48:51], s[56:57]
	s_cmpk_lt_i32 s24, 0x3300
	s_cbranch_scc0 .Lcv_done
	s_waitcnt vmcnt(4)
	s_branch .Lcv_loop
